# K-loop restructured: LDS-DMA issue and pointer SALU interleaved into the MFMA segment, barrier issued 4 MFMAs early with raised priority for the tail, serpentine MFMA order
# speedup vs baseline: 1.0117x; 1.0012x over previous
; #define PG8_STAGE(bufoff, gbase, voff) do { _Pragma("unroll") for (int _i = 0; _i < 2; ++_i) \
;     __builtin_amdgcn_global_load_lds((const unsigned*)((const char*)(gbase) + (voff)[_i]), (LAS unsigned*)(lds + (bufoff) + ldsw + _i * 8192), 16, 0, 0); } while (0)
; #define PG8_LDA(dst, b, h) do { _Pragma("unroll") for (int m = 0; m < 4; ++m) _Pragma("unroll") for (int k = 0; k < 2; ++k) dst[m][k] = *(const LAS bf16x8*)(lds + PG8_SA(b, h) + aoff + m * 2048 + k * 1024); } while (0)
; #define PG8_LDB(dst, b, h) do { _Pragma("unroll") for (int n = 0; n < 2; ++n) _Pragma("unroll") for (int k = 0; k < 2; ++k) dst[n][k] = *(const LAS bf16x8*)(lds + PG8_SB(b, h) + boff + n * 2048 + k * 1024); } while (0)
; #define PG8_MMA(ai, bj, At, Bt) do { __builtin_amdgcn_s_setprio(1); _Pragma("unroll") for (int m = 0; m < 4; ++m) _Pragma("unroll") for (int n = 0; n < 2; ++n) _Pragma("unroll") for (int k = 0; k < 2; ++k) \
;     acc[ai][bj][m][n] = __builtin_amdgcn_mfma_f32_16x16x32_bf16(Bt[n][k], At[m][k], acc[ai][bj][m][n], 0, 0, 0); __builtin_amdgcn_s_setprio(0); } while (0)
; #define PG8_WAIT_V(n) asm volatile("s_waitcnt vmcnt(" #n ")" ::: "memory")
; #define PG8_WAIT_L(n) asm volatile("s_waitcnt lgkmcnt(" #n ")" ::: "memory")
; #define PG8_BAR __builtin_amdgcn_s_barrier()
; __device__ __forceinline__ void gemm_phase(const Ctx& cx, LAS unsigned char* lds, const GemmDesc& g) {
;     ...
;     for (int t = 0; t < nt; t += 2) {
;       const bool last = (t == nt - 2);
;       const char* a1 = ktile_ptr(cA1, cA2, t + 1, ksplit, kstepA);
;       const char* a2 = last ? ktile_ptr(nA1, nA2, 0, ksplit, kstepA) : ktile_ptr(cA1, cA2, t + 2, ksplit, kstepA);
;       const char* a3 = last ? ktile_ptr(nA1, nA2, 1, ksplit, kstepA) : ktile_ptr(cA1, cA2, t + 3, ksplit, kstepA);
;       const char* b2 = last ? nB : cB + (size_t)(t + 2) * kstepB; const char* b3 = b2 + kstepB;
;       PG8_LDB(B0, 0, 0); PG8_LDB(B1, 0, 1); PG8_SCHED; PG8_LDA(At, 0, 0); PG8_STAGE(PG8_SA(1, 1), a1 + hstepA, voffA);
;       PG8_WAIT_V(8); PG8_WAIT_L(0); PG8_BAR; PG8_MMA(0, 0, At, B0); PG8_MMA(0, 1, At, B1); PG8_BAR; PG8_SCHED;
;       PG8_LDA(At, 0, 1); PG8_STAGE(PG8_SB(0, 0), b2, voffB); PG8_STAGE(PG8_SB(0, 1), b2 + hstepB, voffB); PG8_STAGE(PG8_SA(0, 0), a2, voffA);
;       PG8_WAIT_V(8); PG8_WAIT_L(0); PG8_BAR; PG8_MMA(1, 0, At, B0); PG8_MMA(1, 1, At, B1); PG8_BAR; PG8_SCHED;
.LBB0_358:
	s_add_i32 s7, s6, 1
	s_sub_i32 s14, s7, s41
	s_min_u32 s76, s7, s14
	s_cmp_lt_u32 s7, s41
	s_cselect_b32 s7, s9, s17
	s_cselect_b32 s54, s8, s16
	s_lshl_b64 s[14:15], s[76:77], s80
	s_add_u32 s55, s54, s14
	s_addc_u32 s73, s7, s15
	s_add_i32 s76, 0, 0x10000
	v_add_u32_e32 v96, s76, v252
	s_add_i32 vcc_lo, 0, 0x14000
	ds_read_b128 v[130:133], v96
	ds_read_b128 v[134:137], v96 offset:1024
	ds_read_b128 v[138:141], v96 offset:2048
	ds_read_b128 v[142:145], v96 offset:3072
	v_add_u32_e32 v96, vcc_lo, v252
	ds_read_b128 v[146:149], v96
	ds_read_b128 v[150:153], v96 offset:1024
	ds_read_b128 v[154:157], v96 offset:2048
	ds_read_b128 v[158:161], v96 offset:3072
	ds_read_b128 v[162:165], v237
	ds_read_b128 v[166:169], v237 offset:1024
	ds_read_b128 v[170:173], v237 offset:2048
	ds_read_b128 v[174:177], v237 offset:3072
	ds_read_b128 v[178:181], v237 offset:4096
	ds_read_b128 v[182:185], v237 offset:5120
	ds_read_b128 v[186:189], v237 offset:6144
	ds_read_b128 v[190:193], v237 offset:7168
	s_waitcnt vmcnt(6)
	s_barrier
	s_setprio 1
	s_waitcnt lgkmcnt(0)
	v_mfma_f32_16x16x32_bf16 v[126:129], v[130:133], v[162:165], v[126:129]
	v_mfma_f32_16x16x32_bf16 v[126:129], v[134:137], v[166:169], v[126:129]
	s_add_u32 s72, s55, s28
	s_addc_u32 s73, s73, s29
	v_mfma_f32_16x16x32_bf16 v[122:125], v[142:145], v[166:169], v[122:125]
	v_lshl_add_u64 v[194:195], s[72:73], 0, v[210:211]
	s_add_i32 m0, s51, 0xc000
	v_mfma_f32_16x16x32_bf16 v[122:125], v[138:141], v[162:165], v[122:125]
	s_nop 0
	global_load_lds_dwordx4 v[194:195], off
	v_mfma_f32_16x16x32_bf16 v[118:121], v[146:149], v[162:165], v[118:121]
	v_lshl_add_u64 v[194:195], s[72:73], 0, v[212:213]
	s_add_i32 m0, s51, 0xe000
	v_mfma_f32_16x16x32_bf16 v[118:121], v[150:153], v[166:169], v[118:121]
	s_nop 0
	global_load_lds_dwordx4 v[194:195], off
	v_mfma_f32_16x16x32_bf16 v[114:117], v[158:161], v[166:169], v[114:117]
	s_add_i32 s54, s6, 2
	s_cmp_lt_u32 s54, s41
	v_mfma_f32_16x16x32_bf16 v[114:117], v[154:157], v[162:165], v[114:117]
	s_cselect_b64 s[14:15], -1, 0
	s_and_b64 s[58:59], s[14:15], exec
	v_mfma_f32_16x16x32_bf16 v[98:101], v[154:157], v[170:173], v[98:101]
	s_cselect_b32 s7, 0, s41
	s_sub_i32 s7, s6, s7
	v_mfma_f32_16x16x32_bf16 v[98:101], v[158:161], v[174:177], v[98:101]
	s_add_i32 s76, s7, 2
	s_and_b64 s[14:15], s[14:15], exec
	v_mfma_f32_16x16x32_bf16 v[102:105], v[150:153], v[174:177], v[102:105]
	s_cselect_b32 s7, s9, s17
	s_cselect_b32 s58, s8, s16
	v_mfma_f32_16x16x32_bf16 v[102:105], v[146:149], v[170:173], v[102:105]
	s_lshl_b64 s[14:15], s[76:77], s80
	s_add_u32 s72, s58, s14
	v_mfma_f32_16x16x32_bf16 v[106:109], v[138:141], v[170:173], v[106:109]
	s_addc_u32 s7, s7, s15
	s_add_i32 s14, s6, 3
	v_mfma_f32_16x16x32_bf16 v[106:109], v[142:145], v[174:177], v[106:109]
	s_cmp_lt_u32 s14, s41
	s_cselect_b64 s[14:15], -1, 0
	v_mfma_f32_16x16x32_bf16 v[110:113], v[134:137], v[174:177], v[110:113]
	s_and_b64 s[58:59], s[14:15], exec
	s_cselect_b32 s58, 0, s41
	v_mfma_f32_16x16x32_bf16 v[110:113], v[130:133], v[170:173], v[110:113]
	s_sub_i32 s58, s6, s58
	s_add_i32 s76, s58, 3
	v_mfma_f32_16x16x32_bf16 v[92:95], v[130:133], v[178:181], v[92:95]
	s_and_b64 s[14:15], s[14:15], exec
	s_cselect_b32 s58, s9, s17
	v_mfma_f32_16x16x32_bf16 v[92:95], v[134:137], v[182:185], v[92:95]
	s_cselect_b32 s59, s8, s16
	s_lshl_b64 s[14:15], s[76:77], s80
	v_mfma_f32_16x16x32_bf16 v[88:91], v[142:145], v[182:185], v[88:91]
	s_add_u32 s59, s59, s14
	s_addc_u32 s58, s58, s15
	v_mfma_f32_16x16x32_bf16 v[88:91], v[138:141], v[178:181], v[88:91]
	s_cmp_eq_u32 s39, s6
	s_cselect_b32 s15, s13, s7
	v_mfma_f32_16x16x32_bf16 v[84:87], v[146:149], v[178:181], v[84:87]
	s_cselect_b32 s14, s12, s72
	s_cselect_b32 s7, s21, s58
	v_mfma_f32_16x16x32_bf16 v[84:87], v[150:153], v[182:185], v[84:87]
	s_cselect_b32 s6, s20, s59
	s_cselect_b32 s59, s97, s53
	v_mfma_f32_16x16x32_bf16 v[80:83], v[158:161], v[182:185], v[80:83]
	s_cselect_b32 s58, s96, s52
	s_mov_b32 s76, 0x10000
	v_mfma_f32_16x16x32_bf16 v[80:83], v[154:157], v[178:181], v[80:83]
	v_mfma_f32_16x16x32_bf16 v[64:67], v[154:157], v[186:189], v[64:67]
	v_mfma_f32_16x16x32_bf16 v[64:67], v[158:161], v[190:193], v[64:67]
	v_mfma_f32_16x16x32_bf16 v[68:71], v[150:153], v[190:193], v[68:71]
	v_mfma_f32_16x16x32_bf16 v[68:71], v[146:149], v[186:189], v[68:71]
	s_barrier
	s_setprio 2
	v_mfma_f32_16x16x32_bf16 v[72:75], v[138:141], v[186:189], v[72:75]
	v_mfma_f32_16x16x32_bf16 v[72:75], v[142:145], v[190:193], v[72:75]
	v_mfma_f32_16x16x32_bf16 v[76:79], v[134:137], v[190:193], v[76:79]
	v_mfma_f32_16x16x32_bf16 v[76:79], v[130:133], v[186:189], v[76:79]
	s_setprio 0
	ds_read_b128 v[162:165], v237 offset:16384
	ds_read_b128 v[166:169], v237 offset:17408
	ds_read_b128 v[170:173], v237 offset:18432
	ds_read_b128 v[174:177], v237 offset:19456
	ds_read_b128 v[178:181], v237 offset:20480
	ds_read_b128 v[182:185], v237 offset:21504
	ds_read_b128 v[186:189], v237 offset:22528
	ds_read_b128 v[190:193], v237 offset:23552
	s_waitcnt vmcnt(2)
	s_barrier
; #define PG8_STAGE(bufoff, gbase, voff) do { _Pragma("unroll") for (int _i = 0; _i < 2; ++_i) \
;     __builtin_amdgcn_global_load_lds((const unsigned*)((const char*)(gbase) + (voff)[_i]), (LAS unsigned*)(lds + (bufoff) + ldsw + _i * 8192), 16, 0, 0); } while (0)
; #define PG8_LDA(dst, b, h) do { _Pragma("unroll") for (int m = 0; m < 4; ++m) _Pragma("unroll") for (int k = 0; k < 2; ++k) dst[m][k] = *(const LAS bf16x8*)(lds + PG8_SA(b, h) + aoff + m * 2048 + k * 1024); } while (0)
; #define PG8_LDB(dst, b, h) do { _Pragma("unroll") for (int n = 0; n < 2; ++n) _Pragma("unroll") for (int k = 0; k < 2; ++k) dst[n][k] = *(const LAS bf16x8*)(lds + PG8_SB(b, h) + boff + n * 2048 + k * 1024); } while (0)
; #define PG8_MMA(ai, bj, At, Bt) do { __builtin_amdgcn_s_setprio(1); _Pragma("unroll") for (int m = 0; m < 4; ++m) _Pragma("unroll") for (int n = 0; n < 2; ++n) _Pragma("unroll") for (int k = 0; k < 2; ++k) \
;     acc[ai][bj][m][n] = __builtin_amdgcn_mfma_f32_16x16x32_bf16(Bt[n][k], At[m][k], acc[ai][bj][m][n], 0, 0, 0); __builtin_amdgcn_s_setprio(0); } while (0)
; #define PG8_WAIT_V(n) asm volatile("s_waitcnt vmcnt(" #n ")" ::: "memory")
; #define PG8_WAIT_L(n) asm volatile("s_waitcnt lgkmcnt(" #n ")" ::: "memory")
; #define PG8_BAR __builtin_amdgcn_s_barrier()
; #define PG8_SCHED __builtin_amdgcn_sched_barrier(0)
; __device__ __forceinline__ void gemm_phase(const Ctx& cx, LAS unsigned char* lds, const GemmDesc& g) {
;     ...
;       PG8_LDA(At, 0, 1); PG8_STAGE(PG8_SB(0, 0), b2, voffB); PG8_STAGE(PG8_SB(0, 1), b2 + hstepB, voffB); PG8_STAGE(PG8_SA(0, 0), a2, voffA);
;       PG8_WAIT_V(8); PG8_WAIT_L(0); PG8_BAR; PG8_MMA(1, 0, At, B0); PG8_MMA(1, 1, At, B1); PG8_BAR; PG8_SCHED;
;       PG8_LDB(B0, 1, 0); PG8_LDB(B1, 1, 1); PG8_SCHED; PG8_LDA(At, 1, 0); PG8_STAGE(PG8_SA(0, 1), a2 + hstepA, voffA);
;       PG8_WAIT_V(8); PG8_WAIT_L(0); PG8_BAR; PG8_MMA(0, 0, At, B0); PG8_MMA(0, 1, At, B1); PG8_BAR; PG8_SCHED;
	s_setprio 1
	s_waitcnt lgkmcnt(0)
	v_mfma_f32_16x16x32_bf16 v[60:63], v[130:133], v[162:165], v[60:63]
	v_mfma_f32_16x16x32_bf16 v[60:63], v[134:137], v[166:169], v[60:63]
	s_add_i32 s55, s76, s36
	v_mfma_f32_16x16x32_bf16 v[56:59], v[142:145], v[166:169], v[56:59]
	v_lshl_add_u64 v[194:195], s[58:59], 0, v[216:217]
	v_mfma_f32_16x16x32_bf16 v[56:59], v[138:141], v[162:165], v[56:59]
	s_mov_b32 m0, s55
	v_mfma_f32_16x16x32_bf16 v[52:55], v[146:149], v[162:165], v[52:55]
	s_nop 0
	v_mfma_f32_16x16x32_bf16 v[52:55], v[150:153], v[166:169], v[52:55]
	global_load_lds_dwordx4 v[194:195], off
	v_mfma_f32_16x16x32_bf16 v[48:51], v[158:161], v[166:169], v[48:51]
	s_add_i32 m0, s55, 0x2000
	v_mfma_f32_16x16x32_bf16 v[48:51], v[154:157], v[162:165], v[48:51]
	v_lshl_add_u64 v[196:197], s[58:59], 0, v[214:215]
	v_mfma_f32_16x16x32_bf16 v[32:35], v[154:157], v[170:173], v[32:35]
	s_add_u32 s58, s58, s30
	v_mfma_f32_16x16x32_bf16 v[32:35], v[158:161], v[174:177], v[32:35]
	s_addc_u32 s59, s59, s31
	v_mfma_f32_16x16x32_bf16 v[36:39], v[150:153], v[174:177], v[36:39]
	s_add_i32 s55, vcc_lo, s36
	v_mfma_f32_16x16x32_bf16 v[36:39], v[146:149], v[170:173], v[36:39]
	global_load_lds_dwordx4 v[196:197], off
	v_mfma_f32_16x16x32_bf16 v[40:43], v[138:141], v[170:173], v[40:43]
	v_lshl_add_u64 v[198:199], s[58:59], 0, v[216:217]
	v_mfma_f32_16x16x32_bf16 v[40:43], v[142:145], v[174:177], v[40:43]
	s_mov_b32 m0, s55
	v_mfma_f32_16x16x32_bf16 v[44:47], v[134:137], v[174:177], v[44:47]
	v_lshl_add_u64 v[200:201], s[58:59], 0, v[214:215]
	v_mfma_f32_16x16x32_bf16 v[44:47], v[130:133], v[170:173], v[44:47]
	global_load_lds_dwordx4 v[198:199], off
	v_mfma_f32_16x16x32_bf16 v[28:31], v[130:133], v[178:181], v[28:31]
	s_add_i32 m0, s55, 0x2000
	v_mfma_f32_16x16x32_bf16 v[28:31], v[134:137], v[182:185], v[28:31]
	v_lshl_add_u64 v[202:203], s[14:15], 0, v[210:211]
	v_mfma_f32_16x16x32_bf16 v[24:27], v[142:145], v[182:185], v[24:27]
	global_load_lds_dwordx4 v[200:201], off
	v_mfma_f32_16x16x32_bf16 v[24:27], v[138:141], v[178:181], v[24:27]
	s_mov_b32 m0, s51
	v_mfma_f32_16x16x32_bf16 v[20:23], v[146:149], v[178:181], v[20:23]
	s_nop 0
	v_mfma_f32_16x16x32_bf16 v[20:23], v[150:153], v[182:185], v[20:23]
	global_load_lds_dwordx4 v[202:203], off
	v_mfma_f32_16x16x32_bf16 v[16:19], v[158:161], v[182:185], v[16:19]
	v_lshl_add_u64 v[202:203], s[14:15], 0, v[212:213]
	v_mfma_f32_16x16x32_bf16 v[16:19], v[154:157], v[178:181], v[16:19]
	s_mov_b32 m0, s43
	v_mfma_f32_16x16x32_bf16 v[0:3], v[154:157], v[186:189], v[0:3]
	s_nop 0
	v_mfma_f32_16x16x32_bf16 v[0:3], v[158:161], v[190:193], v[0:3]
	global_load_lds_dwordx4 v[202:203], off
	v_mfma_f32_16x16x32_bf16 v[4:7], v[150:153], v[190:193], v[4:7]
	v_mfma_f32_16x16x32_bf16 v[4:7], v[146:149], v[186:189], v[4:7]
	s_barrier
	s_setprio 2
	v_mfma_f32_16x16x32_bf16 v[8:11], v[138:141], v[186:189], v[8:11]
	v_mfma_f32_16x16x32_bf16 v[8:11], v[142:145], v[190:193], v[8:11]
	v_mfma_f32_16x16x32_bf16 v[12:15], v[134:137], v[190:193], v[12:15]
	v_mfma_f32_16x16x32_bf16 v[12:15], v[130:133], v[186:189], v[12:15]
	s_setprio 0
	s_add_i32 s55, 0, 0x18000
	v_add_u32_e32 v96, s55, v252
	s_add_i32 s58, 0, 0x1c000
	ds_read_b128 v[130:133], v96
	ds_read_b128 v[134:137], v96 offset:1024
	ds_read_b128 v[138:141], v96 offset:2048
	ds_read_b128 v[142:145], v96 offset:3072
	v_add_u32_e32 v96, s58, v252
	ds_read_b128 v[146:149], v96
	ds_read_b128 v[150:153], v96 offset:1024
	ds_read_b128 v[154:157], v96 offset:2048
	ds_read_b128 v[158:161], v96 offset:3072
	ds_read_b128 v[162:165], v237 offset:32768
	ds_read_b128 v[166:169], v237 offset:33792
	ds_read_b128 v[170:173], v237 offset:34816
	ds_read_b128 v[174:177], v237 offset:35840
	ds_read_b128 v[178:181], v237 offset:36864
	ds_read_b128 v[182:185], v237 offset:37888
	ds_read_b128 v[186:189], v237 offset:38912
	ds_read_b128 v[190:193], v237 offset:39936
	s_waitcnt vmcnt(6)
	s_barrier
	s_setprio 1
	s_waitcnt lgkmcnt(0)
	v_mfma_f32_16x16x32_bf16 v[126:129], v[130:133], v[162:165], v[126:129]
	v_mfma_f32_16x16x32_bf16 v[126:129], v[134:137], v[166:169], v[126:129]
	s_add_u32 s14, s14, s28
	v_mfma_f32_16x16x32_bf16 v[122:125], v[142:145], v[166:169], v[122:125]
	s_addc_u32 s15, s15, s29
	v_mfma_f32_16x16x32_bf16 v[122:125], v[138:141], v[162:165], v[122:125]
	s_mov_b32 m0, s40
	v_mfma_f32_16x16x32_bf16 v[118:121], v[146:149], v[162:165], v[118:121]
	v_lshl_add_u64 v[202:203], s[14:15], 0, v[210:211]
	v_mfma_f32_16x16x32_bf16 v[118:121], v[150:153], v[166:169], v[118:121]
	global_load_lds_dwordx4 v[202:203], off
	v_mfma_f32_16x16x32_bf16 v[114:117], v[158:161], v[166:169], v[114:117]
	v_lshl_add_u64 v[202:203], s[14:15], 0, v[212:213]
	v_mfma_f32_16x16x32_bf16 v[114:117], v[154:157], v[162:165], v[114:117]
	s_mov_b32 m0, s37
	v_mfma_f32_16x16x32_bf16 v[98:101], v[154:157], v[170:173], v[98:101]
	s_nop 0
	v_mfma_f32_16x16x32_bf16 v[98:101], v[158:161], v[174:177], v[98:101]
	global_load_lds_dwordx4 v[202:203], off
	v_mfma_f32_16x16x32_bf16 v[102:105], v[150:153], v[174:177], v[102:105]
	v_mfma_f32_16x16x32_bf16 v[102:105], v[146:149], v[170:173], v[102:105]
	v_mfma_f32_16x16x32_bf16 v[106:109], v[138:141], v[170:173], v[106:109]
	v_mfma_f32_16x16x32_bf16 v[106:109], v[142:145], v[174:177], v[106:109]
	v_mfma_f32_16x16x32_bf16 v[110:113], v[134:137], v[174:177], v[110:113]
	v_mfma_f32_16x16x32_bf16 v[110:113], v[130:133], v[170:173], v[110:113]
	v_mfma_f32_16x16x32_bf16 v[92:95], v[130:133], v[178:181], v[92:95]
	v_mfma_f32_16x16x32_bf16 v[92:95], v[134:137], v[182:185], v[92:95]
	v_mfma_f32_16x16x32_bf16 v[88:91], v[142:145], v[182:185], v[88:91]
	v_mfma_f32_16x16x32_bf16 v[88:91], v[138:141], v[178:181], v[88:91]
	v_mfma_f32_16x16x32_bf16 v[84:87], v[146:149], v[178:181], v[84:87]
	v_mfma_f32_16x16x32_bf16 v[84:87], v[150:153], v[182:185], v[84:87]
	v_mfma_f32_16x16x32_bf16 v[80:83], v[158:161], v[182:185], v[80:83]
	v_mfma_f32_16x16x32_bf16 v[80:83], v[154:157], v[178:181], v[80:83]
	v_mfma_f32_16x16x32_bf16 v[64:67], v[154:157], v[186:189], v[64:67]
	v_mfma_f32_16x16x32_bf16 v[64:67], v[158:161], v[190:193], v[64:67]
	v_mfma_f32_16x16x32_bf16 v[68:71], v[150:153], v[190:193], v[68:71]
	v_mfma_f32_16x16x32_bf16 v[68:71], v[146:149], v[186:189], v[68:71]
	s_barrier
; #define PG8_STAGE(bufoff, gbase, voff) do { _Pragma("unroll") for (int _i = 0; _i < 2; ++_i) \
;     __builtin_amdgcn_global_load_lds((const unsigned*)((const char*)(gbase) + (voff)[_i]), (LAS unsigned*)(lds + (bufoff) + ldsw + _i * 8192), 16, 0, 0); } while (0)
; #define PG8_LDA(dst, b, h) do { _Pragma("unroll") for (int m = 0; m < 4; ++m) _Pragma("unroll") for (int k = 0; k < 2; ++k) dst[m][k] = *(const LAS bf16x8*)(lds + PG8_SA(b, h) + aoff + m * 2048 + k * 1024); } while (0)
; #define PG8_MMA(ai, bj, At, Bt) do { __builtin_amdgcn_s_setprio(1); _Pragma("unroll") for (int m = 0; m < 4; ++m) _Pragma("unroll") for (int n = 0; n < 2; ++n) _Pragma("unroll") for (int k = 0; k < 2; ++k) \
;     acc[ai][bj][m][n] = __builtin_amdgcn_mfma_f32_16x16x32_bf16(Bt[n][k], At[m][k], acc[ai][bj][m][n], 0, 0, 0); __builtin_amdgcn_s_setprio(0); } while (0)
; #define PG8_WAIT_V(n) asm volatile("s_waitcnt vmcnt(" #n ")" ::: "memory")
; #define PG8_WAIT_L(n) asm volatile("s_waitcnt lgkmcnt(" #n ")" ::: "memory")
; #define PG8_BAR __builtin_amdgcn_s_barrier()
; #define PG8_SCHED __builtin_amdgcn_sched_barrier(0)
; __device__ __forceinline__ void gemm_phase(const Ctx& cx, LAS unsigned char* lds, const GemmDesc& g) {
;     ...
;       PG8_WAIT_V(8); PG8_WAIT_L(0); PG8_BAR; PG8_MMA(0, 0, At, B0); PG8_MMA(0, 1, At, B1); PG8_BAR; PG8_SCHED;
;       PG8_LDA(At, 1, 1); PG8_STAGE(PG8_SB(1, 0), b3, voffB); PG8_STAGE(PG8_SB(1, 1), b3 + hstepB, voffB); PG8_STAGE(PG8_SA(1, 0), a3, voffA);
;       PG8_WAIT_V(8); PG8_WAIT_L(0); PG8_BAR; PG8_MMA(1, 0, At, B0); PG8_MMA(1, 1, At, B1); PG8_BAR; PG8_SCHED;
;     }
;     if (wr == 0) PG8_BAR;
	s_setprio 2
	v_mfma_f32_16x16x32_bf16 v[72:75], v[138:141], v[186:189], v[72:75]
	v_mfma_f32_16x16x32_bf16 v[72:75], v[142:145], v[190:193], v[72:75]
	v_mfma_f32_16x16x32_bf16 v[76:79], v[134:137], v[190:193], v[76:79]
	v_mfma_f32_16x16x32_bf16 v[76:79], v[130:133], v[186:189], v[76:79]
	s_setprio 0
	ds_read_b128 v[162:165], v237 offset:49152
	ds_read_b128 v[166:169], v237 offset:50176
	ds_read_b128 v[170:173], v237 offset:51200
	ds_read_b128 v[174:177], v237 offset:52224
	ds_read_b128 v[178:181], v237 offset:53248
	ds_read_b128 v[182:185], v237 offset:54272
	ds_read_b128 v[186:189], v237 offset:55296
	ds_read_b128 v[190:193], v237 offset:56320
	s_waitcnt vmcnt(2)
	s_barrier
	s_setprio 1
	s_waitcnt lgkmcnt(0)
	v_mfma_f32_16x16x32_bf16 v[60:63], v[130:133], v[162:165], v[60:63]
	v_mfma_f32_16x16x32_bf16 v[60:63], v[134:137], v[166:169], v[60:63]
	s_add_i32 s14, s55, s36
	v_mfma_f32_16x16x32_bf16 v[56:59], v[142:145], v[166:169], v[56:59]
	v_lshl_add_u64 v[194:195], v[194:195], 0, s[92:93]
	v_mfma_f32_16x16x32_bf16 v[56:59], v[138:141], v[162:165], v[56:59]
	s_mov_b32 m0, s14
	v_mfma_f32_16x16x32_bf16 v[52:55], v[146:149], v[162:165], v[52:55]
	s_nop 0
	v_mfma_f32_16x16x32_bf16 v[52:55], v[150:153], v[166:169], v[52:55]
	global_load_lds_dwordx4 v[194:195], off
	v_mfma_f32_16x16x32_bf16 v[48:51], v[158:161], v[166:169], v[48:51]
	v_lshl_add_u64 v[194:195], v[196:197], 0, s[92:93]
	v_mfma_f32_16x16x32_bf16 v[48:51], v[154:157], v[162:165], v[48:51]
	s_add_i32 m0, s14, 0x2000
	v_mfma_f32_16x16x32_bf16 v[32:35], v[154:157], v[170:173], v[32:35]
	s_add_i32 s14, s58, s36
	v_mfma_f32_16x16x32_bf16 v[32:35], v[158:161], v[174:177], v[32:35]
	global_load_lds_dwordx4 v[194:195], off
	v_mfma_f32_16x16x32_bf16 v[36:39], v[150:153], v[174:177], v[36:39]
	v_lshl_add_u64 v[194:195], v[198:199], 0, s[92:93]
	v_mfma_f32_16x16x32_bf16 v[36:39], v[146:149], v[170:173], v[36:39]
	s_mov_b32 m0, s14
	v_mfma_f32_16x16x32_bf16 v[40:43], v[138:141], v[170:173], v[40:43]
	s_nop 0
	v_mfma_f32_16x16x32_bf16 v[40:43], v[142:145], v[174:177], v[40:43]
	global_load_lds_dwordx4 v[194:195], off
	v_mfma_f32_16x16x32_bf16 v[44:47], v[134:137], v[174:177], v[44:47]
	v_lshl_add_u64 v[194:195], v[200:201], 0, s[92:93]
	v_mfma_f32_16x16x32_bf16 v[44:47], v[130:133], v[170:173], v[44:47]
	s_add_i32 m0, s14, 0x2000
	v_mfma_f32_16x16x32_bf16 v[28:31], v[130:133], v[178:181], v[28:31]
	s_nop 0
	v_mfma_f32_16x16x32_bf16 v[28:31], v[134:137], v[182:185], v[28:31]
	global_load_lds_dwordx4 v[194:195], off
	v_mfma_f32_16x16x32_bf16 v[24:27], v[142:145], v[182:185], v[24:27]
	v_lshl_add_u64 v[194:195], s[6:7], 0, v[210:211]
	v_mfma_f32_16x16x32_bf16 v[24:27], v[138:141], v[178:181], v[24:27]
	s_mov_b32 m0, s0
	v_mfma_f32_16x16x32_bf16 v[20:23], v[146:149], v[178:181], v[20:23]
	s_nop 0
	v_mfma_f32_16x16x32_bf16 v[20:23], v[150:153], v[182:185], v[20:23]
	global_load_lds_dwordx4 v[194:195], off
	v_mfma_f32_16x16x32_bf16 v[16:19], v[158:161], v[182:185], v[16:19]
	v_lshl_add_u64 v[194:195], s[6:7], 0, v[212:213]
	v_mfma_f32_16x16x32_bf16 v[16:19], v[154:157], v[178:181], v[16:19]
	s_mov_b32 m0, s1
	v_mfma_f32_16x16x32_bf16 v[0:3], v[154:157], v[186:189], v[0:3]
	s_nop 0
	v_mfma_f32_16x16x32_bf16 v[0:3], v[158:161], v[190:193], v[0:3]
	global_load_lds_dwordx4 v[194:195], off
	v_mfma_f32_16x16x32_bf16 v[4:7], v[150:153], v[190:193], v[4:7]
	v_mfma_f32_16x16x32_bf16 v[4:7], v[146:149], v[186:189], v[4:7]
	s_barrier
	s_setprio 2
	v_mfma_f32_16x16x32_bf16 v[8:11], v[138:141], v[186:189], v[8:11]
	v_mfma_f32_16x16x32_bf16 v[8:11], v[142:145], v[190:193], v[8:11]
	v_mfma_f32_16x16x32_bf16 v[12:15], v[134:137], v[190:193], v[12:15]
	v_mfma_f32_16x16x32_bf16 v[12:15], v[130:133], v[186:189], v[12:15]
	s_setprio 0
	s_add_u32 s52, s52, 0x100
	s_addc_u32 s53, s53, 0
	s_cmp_ge_u32 s54, s10
	s_mov_b32 s6, s54
	s_cbranch_scc0 .LBB0_358
	v_readlane_b32 s6, v255, 19
	v_readlane_b32 s7, v255, 20
	s_and_b64 vcc, exec, s[6:7]
	s_cbranch_vccz .LBB0_361
	s_barrier
